# v28 + wave priority: attention K-loop at s_setprio 1, hosted pre-barrier block at s_setprio 0 so it yields issue slots to the co-resident wave
# baseline (speedup 1.0000x reference)
; #define DMA_K(t, bf) do { if (ABL & 8) break; const char* kb_ = Kt + (size_t)(t) * KSTEP; LAS unsigned char* kd_ = Kl + (bf) * SHM_K + wid * 1024; \
;     glds16(kb_ + voffK, kd_); glds16(kb_ + 128 + voffK, kd_ + 8192); glds16(Pt + (size_t)(t) * PSTEP + voffP, kd_ + 16384); } while (0)
; #define DMA_V(t, bf) do { if (ABL & 8) break; const char* vb_ = Kt + 256 + (size_t)(t) * KSTEP; LAS unsigned char* vd_ = Vl + (bf) * SHM_V + wid * 1024; \
;     glds16(vb_ + voffV, vd_); glds16(vb_ + (size_t)32 * LDKV * 2 + voffV, vd_ + 8192); } while (0)
; #define END_STEP() do { if (!(ABL & 8)) { asm volatile("s_waitcnt vmcnt(0)" ::: "memory"); __syncthreads(); } } while (0)
; #define RESC(a) do { if (__any((a) < 1.f)) { if (hi == 0) al_l[r32] = (a); asm volatile("s_waitcnt lgkmcnt(0)" ::: "memory"); \
;     _Pragma("unroll") for (int d = 0; d < 4; ++d) _Pragma("unroll") for (int r = 0; r < 16; ++r) o[d][r] *= al_l[crow(r, hi)]; } } while (0)
; template <int ABL> __device__ __forceinline__ void attn_unit(int b, int h, int qb, const bf16_t* Q, const bf16_t* KV, const bf16_t* KPE, bf16_t* MG, float* ssqa, LAS unsigned char* L) {
;     ...
;   END_STEP();
;   QK_TILE(Kl, pA0, pA1, pA0, pA1, 1.f, false); PAR_ONLY(pA0, pA1, alA);
;   RESC(alA);
;   END_STEP(); DMA_K(2, 0); DMA_V(1, 1);
;   for (int j = 1; j + 1 < NT; j += 2) {
.LBB0_753:
	s_mov_b32 m0, s59
	v_sub_f32_e32 v1, v36, v140
	v_sub_f32_e32 v2, v37, v140
	v_lshl_add_u64 v[36:37], v[52:53], 0, s[8:9]
	s_mov_b64 s[0:1], 0x80080
	s_waitcnt vmcnt(0)
	s_barrier
	global_load_lds_dwordx4 v[36:37], off
	v_lshl_add_u64 v[36:37], v[52:53], 0, s[0:1]
	s_mov_b32 m0, s60
	s_mov_b64 s[0:1], 0x40100
	global_load_lds_dwordx4 v[36:37], off
	v_lshl_add_u64 v[36:37], v[54:55], 0, s[10:11]
	s_mov_b32 m0, s61
	s_add_i32 s79, s58, 0x4000
	global_load_lds_dwordx4 v[36:37], off
	v_lshl_add_u64 v[36:37], v[142:143], 0, s[0:1]
	s_mov_b32 m0, s79
	s_mov_b64 s[0:1], 0x60100
	s_add_i32 s80, s58, 0x6000
	global_load_lds_dwordx4 v[36:37], off
	v_lshl_add_u64 v[36:37], v[142:143], 0, s[0:1]
	s_mov_b32 m0, s80
	v_exp_f32_e32 v68, v1
	global_load_lds_dwordx4 v[36:37], off
	v_exp_f32_e32 v1, v2
	v_lshlrev_b32_e32 v2, 3, v56
	v_sub_f32_e32 v130, v20, v140
	v_sub_f32_e32 v131, v21, v140
	v_sub_f32_e32 v132, v22, v140
	v_and_b32_e32 v20, 24, v2
	v_and_b32_e32 v21, 0xc0, v62
	v_lshlrev_b32_e32 v22, 1, v56
	s_lshr_b32 s54, s2, 4
	v_and_b32_e32 v22, 32, v22
	v_and_b32_e32 v2, 0x100, v2
	v_add3_u32 v20, 0, v20, v21
	s_and_b32 s0, s54, 7
	v_add3_u32 v167, v20, v22, v2
	v_lshlrev_b32_e32 v2, 7, v57
	s_lshl_b32 s54, s0, 9
	s_add_i32 s0, 0, 0x10000
	v_add3_u32 v2, s86, v2, v58
	v_add_u32_e32 v181, s0, v63
	s_add_i32 s0, 0, 0x12000
	v_lshl_add_u64 v[144:145], s[74:75], 0, v[2:3]
	v_lshlrev_b32_e32 v2, 12, v57
	s_add_u32 s54, s72, s54
	v_lshl_add_u32 v2, s83, 15, v2
	s_addc_u32 s55, s73, 0
	v_or_b32_e32 v2, v2, v58
	s_add_i32 s85, s85, s84
	s_lshl_b32 s72, s82, 1
	v_sub_f32_e32 v38, v38, v140
	v_sub_f32_e32 v39, v39, v140
	v_sub_f32_e32 v40, v40, v140
	v_sub_f32_e32 v41, v41, v140
	v_sub_f32_e32 v42, v42, v140
	v_sub_f32_e32 v43, v43, v140
	v_sub_f32_e32 v44, v44, v140
	v_sub_f32_e32 v36, v45, v140
	v_sub_f32_e32 v37, v46, v140
	v_sub_f32_e32 v45, v47, v140
	v_sub_f32_e32 v46, v48, v140
	v_sub_f32_e32 v47, v49, v140
	v_sub_f32_e32 v48, v50, v140
	v_sub_f32_e32 v49, v51, v140
	v_lshl_add_u64 v[146:147], s[54:55], 0, v[2:3]
	v_add3_u32 v2, s85, v59, v60
	s_and_b32 s72, s72, 0x80
	v_exp_f32_e32 v112, v38
	v_exp_f32_e32 v113, v39
	v_exp_f32_e32 v110, v40
	v_exp_f32_e32 v111, v41
	v_exp_f32_e32 v108, v42
	v_exp_f32_e32 v109, v43
	v_exp_f32_e32 v106, v44
	v_exp_f32_e32 v107, v36
	v_exp_f32_e32 v104, v37
	v_lshl_or_b32 v2, v2, 12, s72
	v_exp_f32_e32 v105, v45
	v_exp_f32_e32 v102, v46
	v_exp_f32_e32 v103, v47
	v_exp_f32_e32 v100, v48
	v_exp_f32_e32 v101, v49
	v_lshl_add_u32 v2, v164, 6, v2
	v_sub_f32_e32 v133, v23, v140
	v_sub_f32_e32 v160, v24, v140
	v_sub_f32_e32 v161, v25, v140
	v_sub_f32_e32 v158, v26, v140
	v_sub_f32_e32 v159, v27, v140
	v_sub_f32_e32 v156, v28, v140
	v_sub_f32_e32 v157, v29, v140
	v_sub_f32_e32 v154, v30, v140
	v_sub_f32_e32 v155, v31, v140
	v_sub_f32_e32 v152, v32, v140
	v_sub_f32_e32 v153, v33, v140
	v_sub_f32_e32 v150, v34, v140
	v_sub_f32_e32 v151, v35, v140
	v_add_u32_e32 v182, s34, v63
	v_add_u32_e32 v183, s0, v63
	v_add_u32_e32 v184, s53, v63
	v_cmp_gt_u32_e64 s[0:1], 32, v56
	v_or_b32_e32 v2, v2, v61
	v_mov_b64_e32 v[66:67], v[18:19]
	v_mov_b64_e32 v[50:51], v[18:19]
	v_mov_b64_e32 v[34:35], v[18:19]
	s_mov_b32 s81, 1
	v_lshl_add_u32 v166, v163, 2, s57
	v_lshl_add_u64 v[148:149], s[54:55], 0, v[2:3]
	v_mov_b32_e32 v2, 0
	v_mov_b64_e32 v[64:65], v[16:17]
	v_mov_b64_e32 v[62:63], v[14:15]
	v_mov_b64_e32 v[60:61], v[12:13]
	v_mov_b64_e32 v[58:59], v[10:11]
	v_mov_b64_e32 v[56:57], v[8:9]
	v_mov_b64_e32 v[54:55], v[6:7]
	v_mov_b64_e32 v[52:53], v[4:5]
	v_mov_b64_e32 v[48:49], v[16:17]
	v_mov_b64_e32 v[46:47], v[14:15]
	v_mov_b64_e32 v[44:45], v[12:13]
	v_mov_b64_e32 v[42:43], v[10:11]
	v_mov_b64_e32 v[40:41], v[8:9]
	v_mov_b64_e32 v[38:39], v[6:7]
	v_mov_b64_e32 v[36:37], v[4:5]
	v_mov_b64_e32 v[32:33], v[16:17]
	v_mov_b64_e32 v[30:31], v[14:15]
	v_mov_b64_e32 v[28:29], v[12:13]
	v_mov_b64_e32 v[26:27], v[10:11]
	v_mov_b64_e32 v[24:25], v[8:9]
	v_mov_b64_e32 v[22:23], v[6:7]
	v_mov_b64_e32 v[20:21], v[4:5]
	s_setprio 1

; template <int NB>
; __device__ __forceinline__ void p0_batch(int it0, int stride, int lane, const P0Ptrs& a) {
;     ...
;     for (int q = 0; q < NB; ++q) {
;         const float gs = d[q].gs; const bool hk = d[q].ks != nullptr;
;         const f32x4 t0 = hk ? s0[q] * gs : (f32x4){gs, gs, gs, gs}, t1 = hk ? s1[q] * gs : (f32x4){gs, gs, gs, gs};
; #pragma unroll
;         for (int i = 0; i < 4; ++i) { v[q][i] *= t0[i]; v[q][4 + i] *= t1[i]; }
.LBB0_759:
	s_setprio 0
	s_add_i32 s98, s87, -1
	s_cmp_gt_u32 s98, 19
	s_cbranch_scc1 .Lcv_predone
	s_waitcnt vmcnt(0)
	s_cmp_gt_u32 s32, 6
	s_cbranch_scc1 .Lcv_nomul
	v_mul_f32_e32 v238, v237, v238
	v_mul_f32_e32 v239, v237, v239
	v_mul_f32_e32 v240, v237, v240
	v_mul_f32_e32 v241, v237, v241
	v_mul_f32_e32 v242, v237, v242
	v_mul_f32_e32 v243, v237, v243
	v_mul_f32_e32 v244, v237, v244
	v_mul_f32_e32 v245, v237, v245

.Lcv_prepdone:
	s_setprio 1
	v_lshl_add_u64 v[112:113], s[28:29], 0, v[146:147]
	s_mov_b64 s[54:55], 0x18fc0000
	s_mov_b32 m0, s78
	v_lshl_add_u64 v[100:101], v[112:113], 0, s[54:55]
	s_add_i32 s98, s87, -1
	s_cmp_gt_u32 s98, 19
	s_cbranch_scc1 .Lcv_wa0
	s_waitcnt vmcnt(2)
	s_branch .Lcv_wad

.LBB0_770:
	s_setprio 0
	s_mov_b32 m0, s79
	v_lshl_add_u64 v[70:71], v[142:143], 0, s[66:67]
	global_load_lds_dwordx4 v[70:71], off
	v_lshl_add_u64 v[70:71], v[142:143], 0, s[68:69]
	s_mov_b32 m0, s80
	s_nop 0
	global_load_lds_dwordx4 v[70:71], off
	ds_read_b128 v[70:73], v178 offset:57344
	ds_read_b128 v[74:77], v178 offset:61440
	s_waitcnt lgkmcnt(0)
	v_mfma_f32_32x32x16_bf16 v[84:99], v[70:73], v[126:129], 0
	ds_read_b128 v[134:137], v179 offset:57344
	ds_read_b128 v[142:145], v179 offset:61440
	v_exp_f32_e32 v172, v130
	v_cvt_pk_bf16_f32 v130, v68, v1
	v_add_f32_e32 v173, 0, v68
	v_mfma_f32_32x32x16_bf16 v[68:83], v[74:77], v[126:129], 0
	v_exp_f32_e32 v174, v131
	v_add_f32_e32 v1, 0, v1
	v_cvt_pk_bf16_f32 v131, v112, v113
	s_waitcnt lgkmcnt(0)
	v_mfma_f32_32x32x16_bf16 v[84:99], v[134:137], v[122:125], v[84:99]
	ds_read_b128 v[126:129], v177 offset:57344
	ds_read_b128 v[146:149], v177 offset:61440
	v_exp_f32_e32 v175, v132
	v_add_f32_e32 v112, 0, v112
	v_cvt_pk_bf16_f32 v132, v110, v111
	v_mfma_f32_32x32x16_bf16 v[68:83], v[142:145], v[122:125], v[68:83]
	v_exp_f32_e32 v177, v133
	v_add_f32_e32 v113, 0, v113
	v_cvt_pk_bf16_f32 v133, v108, v109
	s_waitcnt lgkmcnt(0)
	v_mfma_f32_32x32x16_bf16 v[84:99], v[126:129], v[118:121], v[84:99]
	ds_read_b128 v[122:125], v176 offset:57344
	ds_read_b128 v[134:137], v176 offset:61440
	v_add_f32_e32 v110, v110, v173
	v_permlane32_swap_b32_e32 v130, v132
	v_exp_f32_e32 v160, v160
	v_mfma_f32_32x32x16_bf16 v[68:83], v[146:149], v[118:121], v[68:83]
	v_add_f32_e32 v1, v111, v1
	v_permlane32_swap_b32_e32 v131, v133
	v_exp_f32_e32 v161, v161
	s_waitcnt lgkmcnt(0)
	v_mfma_f32_32x32x16_bf16 v[84:99], v[122:125], v[114:117], v[84:99]
	ds_read_b128 v[118:121], v185
	ds_read_b128 v[126:129], v186
	ds_read_b128 v[142:145], v171
	v_add_f32_e32 v146, v108, v112
	v_cvt_pk_bf16_f32 v108, v106, v107
	v_exp_f32_e32 v158, v158
	v_mfma_f32_32x32x16_bf16 v[68:83], v[134:137], v[114:117], v[68:83]
	v_add_f32_e32 v147, v109, v113
	v_cvt_pk_bf16_f32 v109, v104, v105
	v_exp_f32_e32 v159, v159
	s_waitcnt lgkmcnt(0)
	v_mfma_f32_32x32x16_bf16 v[84:99], v[118:121], v[142:145], v[84:99]
	ds_read_b128 v[112:115], v187
	ds_read_b128 v[122:125], v188
	ds_read_b128 v[134:137], v170
	v_add_f32_e32 v106, v106, v110
	v_cvt_pk_bf16_f32 v110, v102, v103
	v_exp_f32_e32 v156, v156
	v_mfma_f32_32x32x16_bf16 v[68:83], v[126:129], v[142:145], v[68:83]
	v_add_f32_e32 v1, v107, v1
	v_cvt_pk_bf16_f32 v111, v100, v101
	v_exp_f32_e32 v157, v157
	s_waitcnt lgkmcnt(0)
	v_mfma_f32_32x32x16_bf16 v[84:99], v[112:115], v[134:137], v[84:99]
	ds_read_b128 v[116:119], v189
	ds_read_b128 v[126:129], v190
	ds_read_b128 v[142:145], v169
	v_add_f32_e32 v104, v104, v146
	v_permlane32_swap_b32_e32 v108, v110
	v_exp_f32_e32 v107, v154
	v_mfma_f32_32x32x16_bf16 v[68:83], v[122:125], v[134:137], v[68:83]
	v_add_f32_e32 v105, v105, v147
	v_permlane32_swap_b32_e32 v109, v111
	v_exp_f32_e32 v154, v155
	s_waitcnt lgkmcnt(0)
	v_mfma_f32_32x32x16_bf16 v[84:99], v[116:119], v[142:145], v[84:99]
	ds_read_b128 v[112:115], v191
	ds_read_b128 v[120:123], v192
	ds_read_b128 v[134:137], v168
	v_add_f32_e32 v106, v102, v106
	v_cvt_pk_bf16_f32 v102, v172, v174
	v_exp_f32_e32 v152, v152
	v_mfma_f32_32x32x16_bf16 v[68:83], v[126:129], v[142:145], v[68:83]
	v_add_f32_e32 v1, v103, v1
	v_cvt_pk_bf16_f32 v103, v175, v177
	v_exp_f32_e32 v153, v153
	s_waitcnt lgkmcnt(0)
	v_mfma_f32_32x32x16_bf16 v[84:99], v[112:115], v[134:137], v[84:99]
	ds_read_b128 v[116:119], v193
	ds_read_b128 v[124:127], v194
	ds_read_b128 v[142:145], v171 offset:4096
	v_add_f32_e32 v100, v100, v104
	v_cvt_pk_bf16_f32 v104, v160, v161
	v_exp_f32_e32 v128, v150
	v_mfma_f32_32x32x16_bf16 v[68:83], v[120:123], v[134:137], v[68:83]
	v_add_f32_e32 v101, v101, v105
	v_cvt_pk_bf16_f32 v105, v158, v159
	v_exp_f32_e32 v129, v151
	s_waitcnt lgkmcnt(0)
	v_mfma_f32_32x32x16_bf16 v[84:99], v[116:119], v[142:145], v[84:99]
	ds_read_b128 v[120:123], v195
	ds_read_b128 v[134:137], v196
	ds_read_b128 v[146:149], v170 offset:4096
	v_add_f32_e32 v106, v172, v106
	v_add_f32_e32 v1, v174, v1
	v_permlane32_swap_b32_e32 v102, v104
	v_mfma_f32_32x32x16_bf16 v[68:83], v[124:127], v[142:145], v[68:83]
	v_add_f32_e32 v100, v175, v100
	v_add_f32_e32 v101, v177, v101
	v_permlane32_swap_b32_e32 v103, v105
	s_waitcnt lgkmcnt(0)
	v_mfma_f32_32x32x16_bf16 v[84:99], v[120:123], v[146:149], v[84:99]
	ds_read_b128 v[116:119], v197
	ds_read_b128 v[124:127], v198
	ds_read_b128 v[142:145], v169 offset:4096
	v_add_f32_e32 v106, v160, v106
	v_add_f32_e32 v1, v161, v1
	v_cvt_pk_bf16_f32 v112, v156, v157
	v_mfma_f32_32x32x16_bf16 v[68:83], v[134:137], v[146:149], v[68:83]
	v_add_f32_e32 v100, v158, v100
	v_add_f32_e32 v101, v159, v101
	v_cvt_pk_bf16_f32 v113, v107, v154
	s_waitcnt lgkmcnt(0)
	v_mfma_f32_32x32x16_bf16 v[84:99], v[116:119], v[142:145], v[84:99]
	ds_read_b128 v[120:123], v199
	ds_read_b128 v[134:137], v200
	ds_read_b128 v[146:149], v168 offset:4096
	v_add_f32_e32 v106, v156, v106
	v_add_f32_e32 v1, v157, v1
	v_cvt_pk_bf16_f32 v114, v152, v153
	v_mfma_f32_32x32x16_bf16 v[68:83], v[124:127], v[142:145], v[68:83]
	v_add_f32_e32 v100, v107, v100
	v_add_f32_e32 v101, v154, v101
	v_cvt_pk_bf16_f32 v115, v128, v129
	s_waitcnt lgkmcnt(0)
	v_mfma_f32_32x32x16_bf16 v[84:99], v[120:123], v[146:149], v[84:99]
	v_add_f32_e32 v106, v152, v106
	v_add_f32_e32 v1, v153, v1
	v_permlane32_swap_b32_e32 v112, v114
	v_mfma_f32_32x32x16_bf16 v[68:83], v[134:137], v[146:149], v[68:83]
	v_add_f32_e32 v100, v128, v100
	v_add_f32_e32 v101, v129, v101
	v_permlane32_swap_b32_e32 v113, v115
	v_add_f32_e32 v1, v106, v1
	v_add_f32_e32 v100, v100, v101
	v_add_f32_e32 v1, v1, v100
	v_mov_b32_e32 v100, v1
	s_nop 1
	v_permlane32_swap_b32_e32 v1, v100
	v_max_f32_e32 v101, v85, v85
	v_max_f32_e32 v106, v84, v84
	v_max_f32_e32 v101, v106, v101
	v_max3_f32 v106, v86, v87, v69
	v_max3_f32 v101, v101, v68, v70
	v_max3_f32 v101, v101, v71, v88
	v_max3_f32 v106, v106, v90, v91
	v_max3_f32 v101, v101, v89, v72
	v_max3_f32 v106, v106, v74, v75
	v_max3_f32 v101, v101, v73, v92
	v_max3_f32 v106, v106, v94, v95
	v_max3_f32 v101, v101, v93, v76
	v_max3_f32 v106, v106, v78, v79
	v_max3_f32 v101, v101, v77, v96
	v_max3_f32 v106, v106, v98, v99
	v_max3_f32 v101, v101, v97, v80
	v_max3_f32 v106, v106, v82, v83
	v_max3_f32 v101, v101, v81, v106
	v_mov_b32_e32 v106, v101
	s_nop 1
	v_permlane32_swap_b32_e32 v101, v106
	v_max_f32_e32 v106, v106, v106
	v_max_f32_e32 v101, v101, v101
	v_max_f32_e32 v106, v101, v106
	v_sub_f32_e32 v101, v106, v140
	v_cmp_ge_f32_e32 vcc, s3, v101
	s_cmp_lg_u64 vcc, exec
	v_mov_b32_e32 v101, 1.0
	s_cbranch_scc1 .LBB0_795
